# mask index/compare computation moved into diagonal-only block (on top of K prenorm)
# speedup vs baseline: 1.0067x; 1.0067x over previous
; #define LAS __attribute__((address_space(3)))
; #define MFMA16(a, b, c) __builtin_amdgcn_mfma_f32_16x16x32_bf16(a, b, c, 0, 0, 0)
; __device__ __forceinline__ void attn_unit(const Args& c, int l, int b, int h, int qb, float lam, float lam_init, LAS unsigned char* lds) {
;     ...
;             for (int kb = 0; kb < 8; ++kb) {
;                 s[kb] = (f32x4){0.f, 0.f, 0.f, 0.f};
; #pragma unroll
;                 for (int ks = 0; ks < 2; ++ks) { const bf16x8 a = *(const LAS bf16x8*)(Kt + (16 * kb + r) * 136 + m * 64 + ks * 32 + q4 * 8); s[kb] = MFMA16(a, qf[m][ks], s[kb]); }
;             }
;             if (kt == qb) {
;                 const int qpos = 128 * qb + 16 * w + r;
; #pragma unroll
;                 for (int kb = 0; kb < 8; ++kb)
; #pragma unroll
;                     for (int e = 0; e < 4; ++e) if (128 * kt + 16 * kb + 4 * q4 + e > qpos) s[kb][e] = -INFINITY;
;             }
.LBB0_247:
	s_waitcnt lgkmcnt(0)
	s_barrier
	ds_read_b128 v[114:117], v212
	ds_read_b128 v[118:121], v212 offset:64
	v_add_u32_e32 v214, s5, v208
	s_cmp_eq_u32 s22, s35
	s_waitcnt lgkmcnt(0)
	v_mfma_f32_16x16x32_bf16 v[114:117], v[114:117], v[54:57], 0
	ds_read_b128 v[122:125], v212 offset:4416
	v_mfma_f32_16x16x32_bf16 v[114:117], v[118:121], v[50:53], v[114:117]
	ds_read_b128 v[118:121], v212 offset:4352
	s_waitcnt lgkmcnt(0)
	v_mfma_f32_16x16x32_bf16 v[118:121], v[118:121], v[54:57], 0
	ds_read_b128 v[126:129], v212 offset:8768
	v_mfma_f32_16x16x32_bf16 v[118:121], v[122:125], v[50:53], v[118:121]
	ds_read_b128 v[122:125], v212 offset:8704
	s_waitcnt lgkmcnt(0)
	v_mfma_f32_16x16x32_bf16 v[122:125], v[122:125], v[54:57], 0
	ds_read_b128 v[130:133], v212 offset:13120
	v_mfma_f32_16x16x32_bf16 v[122:125], v[126:129], v[50:53], v[122:125]
	ds_read_b128 v[126:129], v212 offset:13056
	s_waitcnt lgkmcnt(0)
	v_mfma_f32_16x16x32_bf16 v[126:129], v[126:129], v[54:57], 0
	ds_read_b128 v[134:137], v212 offset:17472
	v_mfma_f32_16x16x32_bf16 v[126:129], v[130:133], v[50:53], v[126:129]
	ds_read_b128 v[130:133], v212 offset:17408
	s_waitcnt lgkmcnt(0)
	v_mfma_f32_16x16x32_bf16 v[130:133], v[130:133], v[54:57], 0
	ds_read_b128 v[138:141], v212 offset:21824
	v_mfma_f32_16x16x32_bf16 v[130:133], v[134:137], v[50:53], v[130:133]
	ds_read_b128 v[134:137], v212 offset:21760
	s_waitcnt lgkmcnt(0)
	v_mfma_f32_16x16x32_bf16 v[134:137], v[134:137], v[54:57], 0
	ds_read_b128 v[142:145], v212 offset:26176
	v_mfma_f32_16x16x32_bf16 v[134:137], v[138:141], v[50:53], v[134:137]
	ds_read_b128 v[138:141], v212 offset:26112
	s_waitcnt lgkmcnt(0)
	v_mfma_f32_16x16x32_bf16 v[138:141], v[138:141], v[54:57], 0
	ds_read_b128 v[150:153], v212 offset:30528
	s_cselect_b64 s[16:17], -1, 0
	v_mfma_f32_16x16x32_bf16 v[138:141], v[142:145], v[50:53], v[138:141]
	ds_read_b128 v[142:145], v212 offset:30464
	s_cmp_lg_u32 s22, s35
	s_waitcnt lgkmcnt(0)
	v_mfma_f32_16x16x32_bf16 v[142:145], v[142:145], v[54:57], 0
	v_mfma_f32_16x16x32_bf16 v[142:145], v[150:153], v[50:53], v[142:145]
	s_cbranch_scc1 .LBB0_249
	v_add_u32_e32 v245, 2, v214
	v_add_u32_e32 v246, 3, v214
	v_add_u32_e32 v242, 16, v214
	v_add_u32_e32 v241, 17, v214
	v_add_u32_e32 v244, 18, v214
	v_add_u32_e32 v243, 19, v214
	v_add_u32_e32 v237, 32, v214
	v_add_u32_e32 v240, 33, v214
	v_add_u32_e32 v239, 34, v214
	v_add_u32_e32 v238, 35, v214
	v_add_u32_e32 v235, 48, v214
	v_add_u32_e32 v234, 49, v214
	v_add_u32_e32 v233, 50, v214
	v_add_u32_e32 v236, 51, v214
	v_add_u32_e32 v230, 64, v214
	v_add_u32_e32 v229, 0x41, v214
	v_add_u32_e32 v232, 0x42, v214
	v_add_u32_e32 v231, 0x43, v214
	v_add_u32_e32 v225, 0x50, v214
	v_add_u32_e32 v228, 0x51, v214
	v_add_u32_e32 v227, 0x52, v214
	v_add_u32_e32 v226, 0x53, v214
	v_add_u32_e32 v224, 0x60, v214
	v_add_u32_e32 v223, 0x61, v214
	v_add_u32_e32 v222, 0x62, v214
	v_add_u32_e32 v221, 0x63, v214
	v_add_u32_e32 v220, 0x70, v214
	v_add_u32_e32 v219, 0x71, v214
	v_add_u32_e32 v218, 0x72, v214
	v_add_u32_e32 v217, 0x73, v214
	v_cmp_gt_i32_e64 s[44:45], v214, v209
	v_cmp_lt_i32_e64 s[6:7], v214, v209
	v_cmp_le_i32_e32 vcc, v245, v209
	v_cmp_le_i32_e64 s[12:13], v246, v209
	v_cmp_gt_i32_e64 s[94:95], v242, v209
	v_cmp_le_i32_e64 s[96:97], v241, v209
	v_cmp_le_i32_e64 s[10:11], v244, v209
	v_cmp_le_i32_e64 s[8:9], v243, v209
	v_cmp_gt_i32_e64 s[86:87], v237, v209
	v_cmp_le_i32_e64 s[88:89], v240, v209
	v_cmp_le_i32_e64 s[90:91], v239, v209
	v_cmp_le_i32_e64 s[92:93], v238, v209
	v_cmp_gt_i32_e64 s[78:79], v235, v209
	v_cmp_le_i32_e64 s[80:81], v234, v209
	v_cmp_le_i32_e64 s[82:83], v233, v209
	v_cmp_le_i32_e64 s[84:85], v236, v209
	v_cmp_gt_i32_e64 s[70:71], v230, v209
	v_cmp_le_i32_e64 s[72:73], v229, v209
	v_cmp_le_i32_e64 s[74:75], v232, v209
	v_cmp_le_i32_e64 s[76:77], v231, v209
	v_cmp_gt_i32_e64 s[62:63], v225, v209
	v_cmp_le_i32_e64 s[64:65], v228, v209
	v_cmp_le_i32_e64 s[66:67], v227, v209
	v_cmp_le_i32_e64 s[68:69], v226, v209
	v_cmp_gt_i32_e64 s[54:55], v224, v209
	v_cmp_le_i32_e64 s[56:57], v223, v209
	v_cmp_le_i32_e64 s[58:59], v222, v209
	v_cmp_le_i32_e64 s[60:61], v221, v209
	v_cmp_gt_i32_e64 s[46:47], v220, v209
	v_cmp_le_i32_e64 s[48:49], v219, v209
	v_cmp_le_i32_e64 s[50:51], v218, v209
	v_cmp_le_i32_e64 s[52:53], v217, v209
	v_mov_b32_e32 v146, s23
	v_cndmask_b32_e64 v146, v114, v146, s[44:45]
	v_cndmask_b32_e64 v114, v146, v114, s[6:7]
	v_mov_b32_e32 v146, s23
	v_cndmask_b32_e64 v115, v197, v115, s[6:7]
	v_cndmask_b32_e32 v116, v197, v116, vcc
	v_cndmask_b32_e64 v117, v197, v117, s[12:13]
	v_cndmask_b32_e64 v118, v118, v146, s[94:95]
	v_cndmask_b32_e64 v119, v197, v119, s[96:97]
	v_cndmask_b32_e64 v120, v197, v120, s[10:11]
	v_cndmask_b32_e64 v121, v197, v121, s[8:9]
	v_cndmask_b32_e64 v122, v122, v146, s[86:87]
	v_cndmask_b32_e64 v123, v197, v123, s[88:89]
	v_cndmask_b32_e64 v124, v197, v124, s[90:91]
	v_cndmask_b32_e64 v125, v197, v125, s[92:93]
	v_cndmask_b32_e64 v126, v126, v146, s[78:79]
	v_cndmask_b32_e64 v127, v197, v127, s[80:81]
	v_cndmask_b32_e64 v128, v197, v128, s[82:83]
	v_cndmask_b32_e64 v129, v197, v129, s[84:85]
	v_cndmask_b32_e64 v130, v130, v146, s[70:71]
	v_cndmask_b32_e64 v131, v197, v131, s[72:73]
	v_cndmask_b32_e64 v132, v197, v132, s[74:75]
	v_cndmask_b32_e64 v133, v197, v133, s[76:77]
	v_cndmask_b32_e64 v134, v134, v146, s[62:63]
	v_cndmask_b32_e64 v135, v197, v135, s[64:65]
	v_cndmask_b32_e64 v136, v197, v136, s[66:67]
	v_cndmask_b32_e64 v137, v197, v137, s[68:69]
	v_cndmask_b32_e64 v138, v138, v146, s[54:55]
	v_cndmask_b32_e64 v139, v197, v139, s[56:57]
	v_cndmask_b32_e64 v140, v197, v140, s[58:59]
	v_cndmask_b32_e64 v141, v197, v141, s[60:61]
	v_cndmask_b32_e64 v142, v142, v146, s[46:47]
	v_cndmask_b32_e64 v143, v197, v143, s[48:49]
	v_cndmask_b32_e64 v144, v197, v144, s[50:51]
	v_cndmask_b32_e64 v145, v197, v145, s[52:53]
